# P0 prep: odd workgroups transpose weights first, even workgroups convert x rows first (overlap latency-bound and bandwidth-bound work)
# baseline (speedup 1.0000x reference)
; __device__ void phase_prep(const P& p) {
;     ...
;   int tid = opaque_tid(p), lane = tid & 63, wid = tid >> 6;
;   u16* xb = (u16*)(p.ws + OFF_XB);
;   float* rs1 = (float*)(p.ws + OFF_RS1);
;   for (int row = (blockIdx.x * 8 + wid) * 2; row < NTOK; row += gridDim.x * 16) {
;     const float4* src0 = (const float4*)xrow(p, row);
;     const float4* src1 = (const float4*)xrow(p, row + 1);
;     float4 v0[4], v1[4];
; #pragma unroll
;     for (int i = 0; i < 4; ++i) { v0[i] = src0[lane + i * 64]; v1[i] = src1[lane + i * 64]; }
.LBB0_24:
	s_or_b64 exec, exec, s[0:1]
	s_and_b32 s33, s20, 0xffffffc0
	v_mbcnt_lo_u32_b32 v22, -1, 0
	v_mbcnt_hi_u32_b32 v22, -1, v22
	s_add_u32 s72, s34, 0x1f380000
	v_add_u32_e32 v0, s33, v22
	v_ashrrev_i32_e32 v1, 5, v0
	v_writelane_b32 v255, s20, 0
	s_addc_u32 s73, s35, 0
	s_lshl_b32 s0, s2, 4
	v_and_b32_e32 v1, -2, v1
	v_writelane_b32 v255, s0, 1
	v_add_u32_e32 v4, s0, v1
	s_mov_b32 s0, 0x10000
	v_and_b32_e32 v2, 63, v22
	s_bitcmp1_b32 s2, 0
	s_cbranch_scc1 .Lmy_p0_w
.Lmy_p0_x:
	v_cmp_gt_i32_e32 vcc, s0, v4
	s_and_saveexec_b64 s[6:7], vcc
	s_cbranch_execz .LBB0_29
	v_mbcnt_lo_u32_b32 v1, -1, 0
	v_mbcnt_hi_u32_b32 v5, -1, v1
	v_and_b32_e32 v1, 64, v5
	v_add_u32_e32 v6, 64, v1
	v_xor_b32_e32 v1, 32, v5
	v_cmp_lt_i32_e64 s[0:1], v1, v6
	v_xor_b32_e32 v3, 16, v5
	v_xor_b32_e32 v8, 8, v5
	v_cndmask_b32_e64 v1, v5, v1, s[0:1]
	v_cmp_lt_i32_e64 s[0:1], v3, v6
	v_mov_b32_e32 v7, 0
	v_cmp_eq_u32_e32 vcc, 0, v2
	v_cndmask_b32_e64 v3, v5, v3, s[0:1]
	v_cmp_lt_i32_e64 s[0:1], v8, v6
	s_lshl_b32 s3, s70, 4
	v_lshlrev_b32_e32 v1, 2, v1
	v_cndmask_b32_e64 v8, v5, v8, s[0:1]
	v_lshlrev_b32_e32 v11, 2, v8
	v_xor_b32_e32 v8, 4, v5
	v_cmp_lt_i32_e64 s[0:1], v8, v6
	v_lshlrev_b32_e32 v3, 2, v3
	s_mov_b64 s[10:11], 0
	v_cndmask_b32_e64 v8, v5, v8, s[0:1]
	v_lshlrev_b32_e32 v18, 2, v8
	v_xor_b32_e32 v8, 2, v5
	v_cmp_lt_i32_e64 s[0:1], v8, v6
	s_mov_b32 s13, 0x8000
	v_mov_b32_e32 v21, s55
	v_cndmask_b32_e64 v8, v5, v8, s[0:1]
	v_lshlrev_b32_e32 v19, 2, v8
	v_xor_b32_e32 v8, 1, v5
	v_cmp_lt_i32_e64 s[0:1], v8, v6
	v_lshlrev_b32_e32 v6, 3, v2
	v_mov_b32_e32 v23, s53
	v_cndmask_b32_e64 v5, v5, v8, s[0:1]
	v_lshlrev_b32_e32 v20, 2, v5
	v_lshl_add_u64 v[8:9], s[34:35], 0, v[6:7]
	v_mov_b32_e32 v24, s54
	v_mov_b32_e32 v25, s52
	v_lshlrev_b32_e32 v6, 4, v2
	s_mov_b32 s12, 0x3a800000
	s_mov_b32 s16, 0x800000
	s_mov_b32 s17, 0xffff
	v_mov_b32_e32 v10, 0x358637bd
	s_branch .LBB0_27

; __device__ void phase_prep(const P& p) {
;     ...
;   for (int it = blockIdx.x; it < J4; it += gridDim.x) {
;     if (it < J0) {
;       int n0 = (it >> 4) * 64, k0 = (it & 15) * 64;
;       wt_tile(win, 1024, n0, k0, [&](int k, int n) { return p.w_in[(size_t)k * 3104 + n] * p.g_mix[k]; }, tile, tid);
.LBB0_29:
	s_or_b64 exec, exec, s[6:7]
	s_bitcmp1_b32 s2, 0
	s_cbranch_scc1 .LBB0_56
.Lmy_p0_w:
	s_cmpk_gt_i32 s2, 0xc7f
	s_cbranch_scc1 .Lmy_p0_wdone
	v_ashrrev_i32_e32 v4, 6, v0
	s_movk_i32 s0, 0x104
	v_lshlrev_b32_e32 v6, 1, v2
	v_mov_b32_e32 v7, 0
	v_mul_lo_u32 v19, v4, s0
	s_waitcnt lgkmcnt(0)
	v_lshl_add_u64 v[16:17], s[34:35], 0, v[6:7]
	s_mov_b64 s[0:1], 0x1ed00000
	v_lshl_add_u64 v[8:9], v[16:17], 0, s[0:1]
	s_mov_b64 s[0:1], 0x1e200000
	v_lshl_add_u64 v[10:11], v[16:17], 0, s[0:1]
	s_mov_b64 s[0:1], 0x1e000000
	v_lshl_add_u64 v[12:13], v[16:17], 0, s[0:1]
	s_mov_b64 s[0:1], 0x1c600000
	v_lshl_add_u32 v18, v2, 2, 16
	v_lshlrev_b32_e32 v5, 8, v2
	v_lshlrev_b32_e32 v6, 2, v4
	v_lshl_add_u64 v[14:15], v[16:17], 0, s[0:1]
	s_mov_b64 s[0:1], 0x1c000000
	v_add_u32_e32 v1, 8, v4
	v_add_u32_e32 v3, 16, v4
	v_add_u32_e32 v23, 24, v4
	v_add_u32_e32 v24, 32, v4
	v_add_u32_e32 v25, 40, v4
	v_add_u32_e32 v26, 48, v4
	v_add_u32_e32 v27, 56, v4
	v_add3_u32 v28, v18, v5, v6
	v_lshl_add_u64 v[16:17], v[16:17], 0, s[0:1]
	v_ashrrev_i32_e32 v5, 31, v4
	s_lshl_b32 s3, s2, 2
	s_lshl_b32 s10, s70, 2
	s_lshl_b32 s11, s2, 6
	s_lshl_b32 s12, s70, 6
	s_mov_b32 s5, 0
	v_add_u32_e32 v29, v18, v19
	s_movk_i32 s13, 0x1600
	s_movk_i32 s14, 0x2c00
	s_movk_i32 s15, 0x3080
	s_movk_i32 s16, 0x3000
	s_mov_b32 s17, s2
	s_branch .LBB0_32

; __device__ void phase_prep(const P& p) {
;     ...
;   for (int row = (blockIdx.x * 8 + wid) * 2; row < NTOK; row += gridDim.x * 16) {
;     ...
;   for (int it = blockIdx.x; it < J4; it += gridDim.x) {
.Lmy_p0_wdone:
	s_bitcmp1_b32 s2, 0
	s_cbranch_scc0 .LBB0_56
	v_ashrrev_i32_e32 v1, 5, v0
	v_and_b32_e32 v1, -2, v1
	s_lshl_b32 s0, s2, 4
	v_add_u32_e32 v4, s0, v1
	s_mov_b32 s0, 0x10000
	s_branch .Lmy_p0_x
